# S5 step C causal part: KM fragments for an 8-token block loaded in one batch (14 masked loads + 8 token loads, one wait) instead of one serialized L2 load per MFMA
# speedup vs baseline: 1.0092x; 1.0046x over previous
.LBB0_498:
	global_load_dwordx4 v[124:127], v[168:169], off offset:-128
	global_load_dwordx4 v[120:123], v[168:169], off offset:-96
	global_load_dwordx4 v[116:119], v[168:169], off offset:-64
	global_load_dwordx4 v[112:115], v[168:169], off offset:-32
	global_load_dwordx4 v[108:111], v[168:169], off
	global_load_dwordx4 v[104:107], v[168:169], off offset:32
	global_load_dwordx4 v[100:103], v[168:169], off offset:64
	global_load_dwordx4 v[96:99], v[168:169], off offset:96
	v_mov_b32_e32 v241, 0
	v_add_u32_e32 v240, -7, v132
	v_cmp_lt_i32_e32 vcc, -1, v240
	v_lshlrev_b32_e32 v240, 9, v240
	v_lshl_add_u64 v[242:243], v[154:155], 0, v[240:241]
	v_mov_b32_e32 v184, 0
	v_mov_b32_e32 v185, 0
	v_mov_b32_e32 v186, 0
	v_mov_b32_e32 v187, 0
	s_and_saveexec_b64 s[6:7], vcc
	global_load_dwordx4 v[184:187], v[242:243], off
	s_mov_b64 exec, s[6:7]
	v_add_u32_e32 v240, -6, v132
	v_cmp_lt_i32_e32 vcc, -1, v240
	v_lshlrev_b32_e32 v240, 9, v240
	v_lshl_add_u64 v[242:243], v[154:155], 0, v[240:241]
	v_mov_b32_e32 v188, 0
	v_mov_b32_e32 v189, 0
	v_mov_b32_e32 v190, 0
	v_mov_b32_e32 v191, 0
	s_and_saveexec_b64 s[6:7], vcc
	global_load_dwordx4 v[188:191], v[242:243], off
	s_mov_b64 exec, s[6:7]
	v_add_u32_e32 v240, -5, v132
	v_cmp_lt_i32_e32 vcc, -1, v240
	v_lshlrev_b32_e32 v240, 9, v240
	v_lshl_add_u64 v[242:243], v[154:155], 0, v[240:241]
	v_mov_b32_e32 v192, 0
	v_mov_b32_e32 v193, 0
	v_mov_b32_e32 v194, 0
	v_mov_b32_e32 v195, 0
	s_and_saveexec_b64 s[6:7], vcc
	global_load_dwordx4 v[192:195], v[242:243], off
	s_mov_b64 exec, s[6:7]
	v_add_u32_e32 v240, -4, v132
	v_cmp_lt_i32_e32 vcc, -1, v240
	v_lshlrev_b32_e32 v240, 9, v240
	v_lshl_add_u64 v[242:243], v[154:155], 0, v[240:241]
	v_mov_b32_e32 v196, 0
	v_mov_b32_e32 v197, 0
	v_mov_b32_e32 v198, 0
	v_mov_b32_e32 v199, 0
	s_and_saveexec_b64 s[6:7], vcc
	global_load_dwordx4 v[196:199], v[242:243], off
	s_mov_b64 exec, s[6:7]
	v_add_u32_e32 v240, -3, v132
	v_cmp_lt_i32_e32 vcc, -1, v240
	v_lshlrev_b32_e32 v240, 9, v240
	v_lshl_add_u64 v[242:243], v[154:155], 0, v[240:241]
	v_mov_b32_e32 v200, 0
	v_mov_b32_e32 v201, 0
	v_mov_b32_e32 v202, 0
	v_mov_b32_e32 v203, 0
	s_and_saveexec_b64 s[6:7], vcc
	global_load_dwordx4 v[200:203], v[242:243], off
	s_mov_b64 exec, s[6:7]
	v_add_u32_e32 v240, -2, v132
	v_cmp_lt_i32_e32 vcc, -1, v240
	v_lshlrev_b32_e32 v240, 9, v240
	v_lshl_add_u64 v[242:243], v[154:155], 0, v[240:241]
	v_mov_b32_e32 v204, 0
	v_mov_b32_e32 v205, 0
	v_mov_b32_e32 v206, 0
	v_mov_b32_e32 v207, 0
	s_and_saveexec_b64 s[6:7], vcc
	global_load_dwordx4 v[204:207], v[242:243], off
	s_mov_b64 exec, s[6:7]
	v_add_u32_e32 v240, -1, v132
	v_cmp_lt_i32_e32 vcc, -1, v240
	v_lshlrev_b32_e32 v240, 9, v240
	v_lshl_add_u64 v[242:243], v[154:155], 0, v[240:241]
	v_mov_b32_e32 v208, 0
	v_mov_b32_e32 v209, 0
	v_mov_b32_e32 v210, 0
	v_mov_b32_e32 v211, 0
	s_and_saveexec_b64 s[6:7], vcc
	global_load_dwordx4 v[208:211], v[242:243], off
	s_mov_b64 exec, s[6:7]
	v_add_u32_e32 v240, 0, v132
	v_cmp_lt_i32_e32 vcc, -1, v240
	v_lshlrev_b32_e32 v240, 9, v240
	v_lshl_add_u64 v[242:243], v[154:155], 0, v[240:241]
	v_mov_b32_e32 v212, 0
	v_mov_b32_e32 v213, 0
	v_mov_b32_e32 v214, 0
	v_mov_b32_e32 v215, 0
	s_and_saveexec_b64 s[6:7], vcc
	global_load_dwordx4 v[212:215], v[242:243], off
	s_mov_b64 exec, s[6:7]
	v_add_u32_e32 v240, 1, v132
	v_cmp_lt_i32_e32 vcc, -1, v240
	v_lshlrev_b32_e32 v240, 9, v240
	v_lshl_add_u64 v[242:243], v[154:155], 0, v[240:241]
	v_mov_b32_e32 v216, 0
	v_mov_b32_e32 v217, 0
	v_mov_b32_e32 v218, 0
	v_mov_b32_e32 v219, 0
	s_and_saveexec_b64 s[6:7], vcc
	global_load_dwordx4 v[216:219], v[242:243], off
	s_mov_b64 exec, s[6:7]
	v_add_u32_e32 v240, 2, v132
	v_cmp_lt_i32_e32 vcc, -1, v240
	v_lshlrev_b32_e32 v240, 9, v240
	v_lshl_add_u64 v[242:243], v[154:155], 0, v[240:241]
	v_mov_b32_e32 v220, 0
	v_mov_b32_e32 v221, 0
	v_mov_b32_e32 v222, 0
	v_mov_b32_e32 v223, 0
	s_and_saveexec_b64 s[6:7], vcc
	global_load_dwordx4 v[220:223], v[242:243], off
	s_mov_b64 exec, s[6:7]
	v_add_u32_e32 v240, 3, v132
	v_cmp_lt_i32_e32 vcc, -1, v240
	v_lshlrev_b32_e32 v240, 9, v240
	v_lshl_add_u64 v[242:243], v[154:155], 0, v[240:241]
	v_mov_b32_e32 v224, 0
	v_mov_b32_e32 v225, 0
	v_mov_b32_e32 v226, 0
	v_mov_b32_e32 v227, 0
	s_and_saveexec_b64 s[6:7], vcc
	global_load_dwordx4 v[224:227], v[242:243], off
	s_mov_b64 exec, s[6:7]
	v_add_u32_e32 v240, 4, v132
	v_cmp_lt_i32_e32 vcc, -1, v240
	v_lshlrev_b32_e32 v240, 9, v240
	v_lshl_add_u64 v[242:243], v[154:155], 0, v[240:241]
	v_mov_b32_e32 v228, 0
	v_mov_b32_e32 v229, 0
	v_mov_b32_e32 v230, 0
	v_mov_b32_e32 v231, 0
	s_and_saveexec_b64 s[6:7], vcc
	global_load_dwordx4 v[228:231], v[242:243], off
	s_mov_b64 exec, s[6:7]
	v_add_u32_e32 v240, 5, v132
	v_cmp_lt_i32_e32 vcc, -1, v240
	v_lshlrev_b32_e32 v240, 9, v240
	v_lshl_add_u64 v[242:243], v[154:155], 0, v[240:241]
	v_mov_b32_e32 v232, 0
	v_mov_b32_e32 v233, 0
	v_mov_b32_e32 v234, 0
	v_mov_b32_e32 v235, 0
	s_and_saveexec_b64 s[6:7], vcc
	global_load_dwordx4 v[232:235], v[242:243], off
	s_mov_b64 exec, s[6:7]
	v_add_u32_e32 v240, 6, v132
	v_cmp_lt_i32_e32 vcc, -1, v240
	v_lshlrev_b32_e32 v240, 9, v240
	v_lshl_add_u64 v[242:243], v[154:155], 0, v[240:241]
	v_mov_b32_e32 v236, 0
	v_mov_b32_e32 v237, 0
	v_mov_b32_e32 v238, 0
	v_mov_b32_e32 v239, 0
	s_and_saveexec_b64 s[6:7], vcc
	global_load_dwordx4 v[236:239], v[242:243], off
	s_mov_b64 exec, s[6:7]
	s_waitcnt vmcnt(0)
	s_cmp_le_u32 s33, s23
	s_cbranch_scc0 .Lkm_s0
	v_mfma_f32_32x32x16_bf16 v[48:63], v[212:215], v[124:127], v[48:63]
.Lkm_s0:
	s_cmp_le_u32 s33, s24
	s_cbranch_scc0 .Lkm_s1
	v_mfma_f32_32x32x16_bf16 v[32:47], v[220:223], v[124:127], v[32:47]
.Lkm_s1:
	s_cmp_le_u32 s33, s25
	s_cbranch_scc0 .Lkm_s2
	v_mfma_f32_32x32x16_bf16 v[16:31], v[228:231], v[124:127], v[16:31]
.Lkm_s2:
	v_mfma_f32_32x32x16_bf16 v[0:15], v[236:239], v[124:127], v[0:15]
	s_add_i32 s16, s33, 1
	s_cmp_le_u32 s16, s23
	s_cbranch_scc0 .Lkm_s4
	v_mfma_f32_32x32x16_bf16 v[48:63], v[208:211], v[120:123], v[48:63]
.Lkm_s4:
	s_cmp_le_u32 s16, s24
	s_cbranch_scc0 .Lkm_s5
	v_mfma_f32_32x32x16_bf16 v[32:47], v[216:219], v[120:123], v[32:47]
.Lkm_s5:
	s_cmp_le_u32 s16, s25
	s_cbranch_scc0 .Lkm_s6
	v_mfma_f32_32x32x16_bf16 v[16:31], v[224:227], v[120:123], v[16:31]
.Lkm_s6:
	v_mfma_f32_32x32x16_bf16 v[0:15], v[232:235], v[120:123], v[0:15]
	s_add_i32 s16, s33, 2
	s_cmp_le_u32 s16, s23
	s_cbranch_scc0 .Lkm_s8
	v_mfma_f32_32x32x16_bf16 v[48:63], v[204:207], v[116:119], v[48:63]
.Lkm_s8:
	s_cmp_le_u32 s16, s24
	s_cbranch_scc0 .Lkm_s9
	v_mfma_f32_32x32x16_bf16 v[32:47], v[212:215], v[116:119], v[32:47]
.Lkm_s9:
	s_cmp_le_u32 s16, s25
	s_cbranch_scc0 .Lkm_s10
	v_mfma_f32_32x32x16_bf16 v[16:31], v[220:223], v[116:119], v[16:31]
.Lkm_s10:
	v_mfma_f32_32x32x16_bf16 v[0:15], v[228:231], v[116:119], v[0:15]
	s_add_i32 s16, s33, 3
	s_cmp_le_u32 s16, s23
	s_cbranch_scc0 .Lkm_s12
	v_mfma_f32_32x32x16_bf16 v[48:63], v[200:203], v[112:115], v[48:63]
.Lkm_s12:
	s_cmp_le_u32 s16, s24
	s_cbranch_scc0 .Lkm_s13
	v_mfma_f32_32x32x16_bf16 v[32:47], v[208:211], v[112:115], v[32:47]
.Lkm_s13:
	s_cmp_le_u32 s16, s25
	s_cbranch_scc0 .Lkm_s14
	v_mfma_f32_32x32x16_bf16 v[16:31], v[216:219], v[112:115], v[16:31]
.Lkm_s14:
	v_mfma_f32_32x32x16_bf16 v[0:15], v[224:227], v[112:115], v[0:15]
	s_add_i32 s16, s33, 4
	s_cmp_le_u32 s16, s23
	s_cbranch_scc0 .Lkm_s16
	v_mfma_f32_32x32x16_bf16 v[48:63], v[196:199], v[108:111], v[48:63]
.Lkm_s16:
	s_cmp_le_u32 s16, s24
	s_cbranch_scc0 .Lkm_s17
	v_mfma_f32_32x32x16_bf16 v[32:47], v[204:207], v[108:111], v[32:47]
.Lkm_s17:
	s_cmp_le_u32 s16, s25
	s_cbranch_scc0 .Lkm_s18
	v_mfma_f32_32x32x16_bf16 v[16:31], v[212:215], v[108:111], v[16:31]
.Lkm_s18:
	v_mfma_f32_32x32x16_bf16 v[0:15], v[220:223], v[108:111], v[0:15]
	s_add_i32 s16, s33, 5
	s_cmp_le_u32 s16, s23
	s_cbranch_scc0 .Lkm_s20
	v_mfma_f32_32x32x16_bf16 v[48:63], v[192:195], v[104:107], v[48:63]
.Lkm_s20:
	s_cmp_le_u32 s16, s24
	s_cbranch_scc0 .Lkm_s21
	v_mfma_f32_32x32x16_bf16 v[32:47], v[200:203], v[104:107], v[32:47]
.Lkm_s21:
	s_cmp_le_u32 s16, s25
	s_cbranch_scc0 .Lkm_s22
	v_mfma_f32_32x32x16_bf16 v[16:31], v[208:211], v[104:107], v[16:31]
.Lkm_s22:
	v_mfma_f32_32x32x16_bf16 v[0:15], v[216:219], v[104:107], v[0:15]
	s_add_i32 s16, s33, 6
	s_cmp_le_u32 s16, s23
	s_cbranch_scc0 .Lkm_s24
	v_mfma_f32_32x32x16_bf16 v[48:63], v[188:191], v[100:103], v[48:63]
.Lkm_s24:
	s_cmp_le_u32 s16, s24
	s_cbranch_scc0 .Lkm_s25
	v_mfma_f32_32x32x16_bf16 v[32:47], v[196:199], v[100:103], v[32:47]
.Lkm_s25:
	s_cmp_le_u32 s16, s25
	s_cbranch_scc0 .Lkm_s26
	v_mfma_f32_32x32x16_bf16 v[16:31], v[204:207], v[100:103], v[16:31]
.Lkm_s26:
	v_mfma_f32_32x32x16_bf16 v[0:15], v[212:215], v[100:103], v[0:15]
	s_add_i32 s16, s33, 7
	s_cmp_le_u32 s16, s23
	s_cbranch_scc0 .Lkm_s28
	v_mfma_f32_32x32x16_bf16 v[48:63], v[184:187], v[96:99], v[48:63]
.Lkm_s28:
	s_cmp_le_u32 s16, s24
	s_cbranch_scc0 .Lkm_s29
	v_mfma_f32_32x32x16_bf16 v[32:47], v[192:195], v[96:99], v[32:47]
.Lkm_s29:
	s_cmp_le_u32 s16, s25
	s_cbranch_scc0 .Lkm_s30
	v_mfma_f32_32x32x16_bf16 v[16:31], v[200:203], v[96:99], v[16:31]
.Lkm_s30:
	v_mfma_f32_32x32x16_bf16 v[0:15], v[208:211], v[96:99], v[0:15]
	s_add_i32 s33, s33, 8
	v_add_u32_e32 v132, -8, v132
	s_cmp_gt_u32 s33, s22
	v_lshl_add_u64 v[168:169], v[168:169], 0, s[14:15]
	s_cbranch_scc1 .LBB0_494
	s_branch .LBB0_498
